# GU K-loop: first two counted waits of the first K-iteration after an epilogue relaxed to vmcnt(16) so the 8 epilogue H stores may stay in flight (what those waits retire was issued before the stores)
# baseline (speedup 1.0000x reference)
; #define PG8_STAGE(bufoff, gbase, voff) do { _Pragma("unroll") for (int _i = 0; _i < 2; ++_i) \
;         __builtin_amdgcn_global_load_lds((const unsigned*)((const char*)(gbase) + (voff)[_i]), (PG8_LAS unsigned*)(lds + (bufoff) + ldsw + _i * 8192), 16, 0, 0); } while (0)
; #define PG8_LDA(dst, b, h) do { _Pragma("unroll") for (int m = 0; m < 4; ++m) _Pragma("unroll") for (int k = 0; k < 2; ++k) dst[m][k] = *(const PG8_LAS bf16x8*)(lds + PG8_SA(b, h) + aoff + m * 2048 + k * 1024); } while (0)
; #define PG8_LDB(dst, b, h) do { _Pragma("unroll") for (int n = 0; n < 2; ++n) _Pragma("unroll") for (int k = 0; k < 2; ++k) dst[n][k] = *(const PG8_LAS bf16x8*)(lds + PG8_SB(b, h) + boff + n * 2048 + k * 1024); } while (0)
; #define PG8_MMA(ai, bj, At, Bt) do { __builtin_amdgcn_s_setprio(1); _Pragma("unroll") for (int m = 0; m < 4; ++m) _Pragma("unroll") for (int n = 0; n < 2; ++n) _Pragma("unroll") for (int k = 0; k < 2; ++k) \
;         acc[ai][bj][m][n] = __builtin_amdgcn_mfma_f32_16x16x32_bf16(Bt[n][k], At[m][k], acc[ai][bj][m][n], 0, 0, 0); __builtin_amdgcn_s_setprio(0); } while (0)
; #define PG8_WAIT_V(n) asm volatile("s_waitcnt vmcnt(" #n ")" ::: "memory")
; #define PG8_WAIT_L(n) asm volatile("s_waitcnt lgkmcnt(" #n ")" ::: "memory")
; #define PG8_BAR __builtin_amdgcn_s_barrier()
; #define PG8_SCHED __builtin_amdgcn_sched_barrier(0)
; template <class Epi, class Sched, bool ALIGN_EPI = false, bool SP2 = false>
; __device__ __forceinline__ void gemm_phase(PG8_LAS unsigned char* lds, const Gemm g, const Sched& S, const Epi& E) {
;     ...
;             PG8_LDB(B0, 0, 0); PG8_LDB(B1, 0, 1); PG8_SCHED; PG8_LDA(At, 0, 0); PG8_STAGE(PG8_SA(1, 1), a1 + hstep, voffA);
;             PG8_WAIT_V(8); PG8_WAIT_L(0); PG8_BAR; PG8_MMA(0, 0, At, B0); PG8_MMA(0, 1, At, B1); PG8_BAR; PG8_SCHED;
;             PG8_LDA(At, 0, 1); PG8_STAGE(PG8_SB(0, 0), b2, voffB); PG8_STAGE(PG8_SB(0, 1), b2 + hstep, voffB); PG8_STAGE(PG8_SA(0, 0), a2, voffA);
;             PG8_WAIT_V(8); PG8_WAIT_L(0); PG8_BAR; PG8_MMA(1, 0, At, B0); PG8_MMA(1, 1, At, B1); PG8_BAR; PG8_SCHED;
.LBB0_568:
	s_add_u32 s23, s54, 0xfffc0080
	s_addc_u32 s56, s55, -1
	s_add_i32 s80, 0, 0x10000
	s_cmp_eq_u32 s79, 12
	s_cselect_b32 s59, s15, s56
	s_cselect_b32 s58, s41, s23
	s_cselect_b32 s57, s47, s78
	s_cselect_b32 s56, s49, s75
	s_add_i32 s23, 0, 0x14000
	v_add_u32_e32 v148, s80, v187
	v_add_u32_e32 v176, s23, v187
	ds_read_b128 v[136:139], v148
	ds_read_b128 v[140:143], v148 offset:1024
	ds_read_b128 v[144:147], v148 offset:2048
	ds_read_b128 v[148:151], v148 offset:3072
	ds_read_b128 v[152:155], v176
	ds_read_b128 v[156:159], v176 offset:1024
	ds_read_b128 v[172:175], v176 offset:2048
	ds_read_b128 v[176:179], v176 offset:3072
	v_lshl_add_u64 v[184:185], s[54:55], 0, v[168:169]
	s_add_i32 m0, s64, 0xc000
	ds_read_b128 v[180:183], v191
	ds_read_b128 v[192:195], v191 offset:1024
	ds_read_b128 v[196:199], v191 offset:2048
	ds_read_b128 v[212:215], v191 offset:3072
	ds_read_b128 v[216:219], v191 offset:4096
	ds_read_b128 v[220:223], v191 offset:5120
	ds_read_b128 v[224:227], v191 offset:6144
	ds_read_b128 v[242:245], v191 offset:7168
	global_load_lds_dwordx4 v[184:185], off
	v_lshl_add_u64 v[184:185], s[54:55], 0, v[170:171]
	s_add_i32 m0, s64, 0xe000
	s_nop 0
	global_load_lds_dwordx4 v[184:185], off
	s_cmp_lg_u32 s79, -2
	s_cbranch_scc1 .Lgw0_8
	s_cmp_lt_u32 s73, 2
	s_cbranch_scc1 .Lgw0_8
	s_waitcnt vmcnt(16)
	s_branch .Lgw0_d
.Lgw0_8:
	s_waitcnt vmcnt(8)
.Lgw0_d:
	s_waitcnt lgkmcnt(0)
	s_barrier
	s_setprio 1
	s_waitcnt lgkmcnt(0)
	v_mfma_f32_16x16x32_bf16 v[132:135], v[136:139], v[180:183], v[132:135]
	v_mfma_f32_16x16x32_bf16 v[124:127], v[144:147], v[180:183], v[124:127]
	v_mfma_f32_16x16x32_bf16 v[116:119], v[136:139], v[196:199], v[116:119]
	v_mfma_f32_16x16x32_bf16 v[108:111], v[144:147], v[196:199], v[108:111]
	v_mfma_f32_16x16x32_bf16 v[100:103], v[136:139], v[216:219], v[100:103]
	v_mfma_f32_16x16x32_bf16 v[92:95], v[144:147], v[216:219], v[92:95]
	v_mfma_f32_16x16x32_bf16 v[84:87], v[136:139], v[224:227], v[84:87]
	v_mfma_f32_16x16x32_bf16 v[76:79], v[144:147], v[224:227], v[76:79]
	v_mfma_f32_16x16x32_bf16 v[132:135], v[140:143], v[192:195], v[132:135]
	v_mfma_f32_16x16x32_bf16 v[124:127], v[148:151], v[192:195], v[124:127]
	v_mfma_f32_16x16x32_bf16 v[116:119], v[140:143], v[212:215], v[116:119]
	v_mfma_f32_16x16x32_bf16 v[108:111], v[148:151], v[212:215], v[108:111]
	v_mfma_f32_16x16x32_bf16 v[100:103], v[140:143], v[220:223], v[100:103]
	v_mfma_f32_16x16x32_bf16 v[92:95], v[148:151], v[220:223], v[92:95]
	v_mfma_f32_16x16x32_bf16 v[84:87], v[140:143], v[242:245], v[84:87]
	v_mfma_f32_16x16x32_bf16 v[76:79], v[148:151], v[242:245], v[76:79]
	s_setprio 0
	s_setprio 1
	v_mfma_f32_16x16x32_bf16 v[128:131], v[152:155], v[180:183], v[128:131]
	v_mfma_f32_16x16x32_bf16 v[120:123], v[172:175], v[180:183], v[120:123]
	v_mfma_f32_16x16x32_bf16 v[112:115], v[152:155], v[196:199], v[112:115]
	v_mfma_f32_16x16x32_bf16 v[104:107], v[172:175], v[196:199], v[104:107]
	v_mfma_f32_16x16x32_bf16 v[96:99], v[152:155], v[216:219], v[96:99]
	v_mfma_f32_16x16x32_bf16 v[88:91], v[172:175], v[216:219], v[88:91]
	v_mfma_f32_16x16x32_bf16 v[80:83], v[152:155], v[224:227], v[80:83]
	v_mfma_f32_16x16x32_bf16 v[72:75], v[172:175], v[224:227], v[72:75]
	v_mfma_f32_16x16x32_bf16 v[128:131], v[156:159], v[192:195], v[128:131]
	v_mfma_f32_16x16x32_bf16 v[120:123], v[176:179], v[192:195], v[120:123]
	v_mfma_f32_16x16x32_bf16 v[112:115], v[156:159], v[212:215], v[112:115]
	v_mfma_f32_16x16x32_bf16 v[104:107], v[176:179], v[212:215], v[104:107]
	v_mfma_f32_16x16x32_bf16 v[96:99], v[156:159], v[220:223], v[96:99]
	v_mfma_f32_16x16x32_bf16 v[88:91], v[176:179], v[220:223], v[88:91]
	v_mfma_f32_16x16x32_bf16 v[80:83], v[156:159], v[242:245], v[80:83]
	v_mfma_f32_16x16x32_bf16 v[72:75], v[176:179], v[242:245], v[72:75]
	s_setprio 0
	s_barrier
	s_add_i32 s80, s80, s62
	v_lshl_add_u64 v[184:185], s[56:57], 0, v[162:163]
	s_mov_b32 m0, s80
	ds_read_b128 v[180:183], v191 offset:16384
	ds_read_b128 v[192:195], v191 offset:17408
	ds_read_b128 v[196:199], v191 offset:18432
	ds_read_b128 v[212:215], v191 offset:19456
	ds_read_b128 v[216:219], v191 offset:20480
	ds_read_b128 v[220:223], v191 offset:21504
	ds_read_b128 v[224:227], v191 offset:22528
	ds_read_b128 v[242:245], v191 offset:23552
	global_load_lds_dwordx4 v[184:185], off
	s_add_i32 m0, s80, 0x2000
	s_add_u32 s80, s56, 0x40000
	v_lshl_add_u64 v[238:239], s[56:57], 0, v[2:3]
	s_addc_u32 s81, s57, 0
	s_add_i32 s23, s23, s62
	global_load_lds_dwordx4 v[238:239], off
	v_lshl_add_u64 v[240:241], s[80:81], 0, v[162:163]
	s_mov_b32 m0, s23
	v_lshl_add_u64 v[246:247], s[58:59], 0, v[160:161]
	global_load_lds_dwordx4 v[240:241], off
	v_lshl_add_u64 v[240:241], s[80:81], 0, v[2:3]
	s_add_i32 m0, s23, 0x2000
	s_nop 0
	global_load_lds_dwordx4 v[240:241], off
	v_lshl_add_u64 v[240:241], s[58:59], 0, v[164:165]
	s_mov_b32 m0, s64
	s_nop 0
	global_load_lds_dwordx4 v[240:241], off
	s_mov_b32 m0, s65
	s_nop 0
	global_load_lds_dwordx4 v[246:247], off
	s_cmp_lg_u32 s79, -2
	s_cbranch_scc1 .Lgw1_8
	s_cmp_lt_u32 s73, 2
	s_cbranch_scc1 .Lgw1_8
	s_waitcnt vmcnt(16)
	s_branch .Lgw1_d

; #define PG8_STAGE(bufoff, gbase, voff) do { _Pragma("unroll") for (int _i = 0; _i < 2; ++_i) \
;         __builtin_amdgcn_global_load_lds((const unsigned*)((const char*)(gbase) + (voff)[_i]), (PG8_LAS unsigned*)(lds + (bufoff) + ldsw + _i * 8192), 16, 0, 0); } while (0)
; #define PG8_LDA(dst, b, h) do { _Pragma("unroll") for (int m = 0; m < 4; ++m) _Pragma("unroll") for (int k = 0; k < 2; ++k) dst[m][k] = *(const PG8_LAS bf16x8*)(lds + PG8_SA(b, h) + aoff + m * 2048 + k * 1024); } while (0)
; #define PG8_LDB(dst, b, h) do { _Pragma("unroll") for (int n = 0; n < 2; ++n) _Pragma("unroll") for (int k = 0; k < 2; ++k) dst[n][k] = *(const PG8_LAS bf16x8*)(lds + PG8_SB(b, h) + boff + n * 2048 + k * 1024); } while (0)
; #define PG8_MMA(ai, bj, At, Bt) do { __builtin_amdgcn_s_setprio(1); _Pragma("unroll") for (int m = 0; m < 4; ++m) _Pragma("unroll") for (int n = 0; n < 2; ++n) _Pragma("unroll") for (int k = 0; k < 2; ++k) \
;         acc[ai][bj][m][n] = __builtin_amdgcn_mfma_f32_16x16x32_bf16(Bt[n][k], At[m][k], acc[ai][bj][m][n], 0, 0, 0); __builtin_amdgcn_s_setprio(0); } while (0)
; #define PG8_WAIT_V(n) asm volatile("s_waitcnt vmcnt(" #n ")" ::: "memory")
; #define PG8_WAIT_L(n) asm volatile("s_waitcnt lgkmcnt(" #n ")" ::: "memory")
; #define PG8_BAR __builtin_amdgcn_s_barrier()
; #define PG8_SCHED __builtin_amdgcn_sched_barrier(0)
; template <class Epi, class Sched, bool ALIGN_EPI = false, bool SP2 = false>
; __device__ __forceinline__ void gemm_phase(PG8_LAS unsigned char* lds, const Gemm g, const Sched& S, const Epi& E) {
;     ...
;             PG8_WAIT_V(8); PG8_WAIT_L(0); PG8_BAR; PG8_MMA(1, 0, At, B0); PG8_MMA(1, 1, At, B1); PG8_BAR; PG8_SCHED;
;             PG8_LDB(B0, 1, 0); PG8_LDB(B1, 1, 1); PG8_SCHED; PG8_LDA(At, 1, 0); PG8_STAGE(PG8_SA(0, 1), a2 + hstep, voffA);
;             PG8_WAIT_V(8); PG8_WAIT_L(0); PG8_BAR; PG8_MMA(0, 0, At, B0); PG8_MMA(0, 1, At, B1); PG8_BAR; PG8_SCHED;
.Lgw1_d:
	s_waitcnt lgkmcnt(0)
	s_barrier
	s_setprio 1
	s_waitcnt lgkmcnt(0)
	v_mfma_f32_16x16x32_bf16 v[68:71], v[136:139], v[180:183], v[68:71]
	v_mfma_f32_16x16x32_bf16 v[60:63], v[144:147], v[180:183], v[60:63]
	v_mfma_f32_16x16x32_bf16 v[52:55], v[136:139], v[196:199], v[52:55]
	v_mfma_f32_16x16x32_bf16 v[44:47], v[144:147], v[196:199], v[44:47]
	v_mfma_f32_16x16x32_bf16 v[36:39], v[136:139], v[216:219], v[36:39]
	v_mfma_f32_16x16x32_bf16 v[28:31], v[144:147], v[216:219], v[28:31]
	v_mfma_f32_16x16x32_bf16 v[20:23], v[136:139], v[224:227], v[20:23]
	v_mfma_f32_16x16x32_bf16 v[12:15], v[144:147], v[224:227], v[12:15]
	v_mfma_f32_16x16x32_bf16 v[68:71], v[140:143], v[192:195], v[68:71]
	v_mfma_f32_16x16x32_bf16 v[60:63], v[148:151], v[192:195], v[60:63]
	v_mfma_f32_16x16x32_bf16 v[52:55], v[140:143], v[212:215], v[52:55]
	v_mfma_f32_16x16x32_bf16 v[44:47], v[148:151], v[212:215], v[44:47]
	v_mfma_f32_16x16x32_bf16 v[36:39], v[140:143], v[220:223], v[36:39]
	v_mfma_f32_16x16x32_bf16 v[28:31], v[148:151], v[220:223], v[28:31]
	v_mfma_f32_16x16x32_bf16 v[20:23], v[140:143], v[242:245], v[20:23]
	v_mfma_f32_16x16x32_bf16 v[12:15], v[148:151], v[242:245], v[12:15]
	s_setprio 0
	s_setprio 1
	v_mfma_f32_16x16x32_bf16 v[64:67], v[152:155], v[180:183], v[64:67]
	v_mfma_f32_16x16x32_bf16 v[56:59], v[172:175], v[180:183], v[56:59]
	v_mfma_f32_16x16x32_bf16 v[48:51], v[152:155], v[196:199], v[48:51]
	v_mfma_f32_16x16x32_bf16 v[40:43], v[172:175], v[196:199], v[40:43]
	v_mfma_f32_16x16x32_bf16 v[32:35], v[152:155], v[216:219], v[32:35]
	v_mfma_f32_16x16x32_bf16 v[24:27], v[172:175], v[216:219], v[24:27]
	v_mfma_f32_16x16x32_bf16 v[16:19], v[152:155], v[224:227], v[16:19]
	v_mfma_f32_16x16x32_bf16 v[8:11], v[172:175], v[224:227], v[8:11]
	v_mfma_f32_16x16x32_bf16 v[64:67], v[156:159], v[192:195], v[64:67]
	v_mfma_f32_16x16x32_bf16 v[56:59], v[176:179], v[192:195], v[56:59]
	v_mfma_f32_16x16x32_bf16 v[48:51], v[156:159], v[212:215], v[48:51]
	v_mfma_f32_16x16x32_bf16 v[40:43], v[176:179], v[212:215], v[40:43]
	v_mfma_f32_16x16x32_bf16 v[32:35], v[156:159], v[220:223], v[32:35]
	v_mfma_f32_16x16x32_bf16 v[24:27], v[176:179], v[220:223], v[24:27]
	v_mfma_f32_16x16x32_bf16 v[16:19], v[156:159], v[242:245], v[16:19]
	v_mfma_f32_16x16x32_bf16 v[8:11], v[176:179], v[242:245], v[8:11]
	s_setprio 0
	s_barrier
	s_add_i32 s23, 0, 0x18000
	s_add_i32 s80, 0, 0x1c000
	v_add_u32_e32 v148, s23, v187
	v_add_u32_e32 v176, s80, v187
	ds_read_b128 v[136:139], v148
	ds_read_b128 v[140:143], v148 offset:1024
	ds_read_b128 v[144:147], v148 offset:2048
	ds_read_b128 v[148:151], v148 offset:3072
	ds_read_b128 v[152:155], v176
	ds_read_b128 v[156:159], v176 offset:1024
	ds_read_b128 v[172:175], v176 offset:2048
	ds_read_b128 v[176:179], v176 offset:3072
	s_add_u32 s58, s58, 0x40000
	s_addc_u32 s59, s59, 0
	s_mov_b32 m0, s66
	v_lshl_add_u64 v[248:249], s[58:59], 0, v[164:165]
	ds_read_b128 v[180:183], v191 offset:32768
	ds_read_b128 v[192:195], v191 offset:33792
	ds_read_b128 v[196:199], v191 offset:34816
	ds_read_b128 v[212:215], v191 offset:35840
	ds_read_b128 v[216:219], v191 offset:36864
	ds_read_b128 v[220:223], v191 offset:37888
	ds_read_b128 v[224:227], v191 offset:38912
	ds_read_b128 v[242:245], v191 offset:39936
	global_load_lds_dwordx4 v[248:249], off
	v_lshl_add_u64 v[248:249], s[58:59], 0, v[160:161]
	s_mov_b32 m0, s67
	s_nop 0
	global_load_lds_dwordx4 v[248:249], off
	s_waitcnt vmcnt(8)
	s_waitcnt lgkmcnt(0)
	s_barrier
	s_setprio 1
	s_waitcnt lgkmcnt(0)
	v_mfma_f32_16x16x32_bf16 v[132:135], v[136:139], v[180:183], v[132:135]
	v_mfma_f32_16x16x32_bf16 v[124:127], v[144:147], v[180:183], v[124:127]
	v_mfma_f32_16x16x32_bf16 v[116:119], v[136:139], v[196:199], v[116:119]
	v_mfma_f32_16x16x32_bf16 v[108:111], v[144:147], v[196:199], v[108:111]
	v_mfma_f32_16x16x32_bf16 v[100:103], v[136:139], v[216:219], v[100:103]
	v_mfma_f32_16x16x32_bf16 v[92:95], v[144:147], v[216:219], v[92:95]
	v_mfma_f32_16x16x32_bf16 v[84:87], v[136:139], v[224:227], v[84:87]
	v_mfma_f32_16x16x32_bf16 v[76:79], v[144:147], v[224:227], v[76:79]
	v_mfma_f32_16x16x32_bf16 v[132:135], v[140:143], v[192:195], v[132:135]
	v_mfma_f32_16x16x32_bf16 v[124:127], v[148:151], v[192:195], v[124:127]
	v_mfma_f32_16x16x32_bf16 v[116:119], v[140:143], v[212:215], v[116:119]
	v_mfma_f32_16x16x32_bf16 v[108:111], v[148:151], v[212:215], v[108:111]
	v_mfma_f32_16x16x32_bf16 v[100:103], v[140:143], v[220:223], v[100:103]
	v_mfma_f32_16x16x32_bf16 v[92:95], v[148:151], v[220:223], v[92:95]
	v_mfma_f32_16x16x32_bf16 v[84:87], v[140:143], v[242:245], v[84:87]
	v_mfma_f32_16x16x32_bf16 v[76:79], v[148:151], v[242:245], v[76:79]
	s_setprio 0
	s_setprio 1
	v_mfma_f32_16x16x32_bf16 v[128:131], v[152:155], v[180:183], v[128:131]
	v_mfma_f32_16x16x32_bf16 v[120:123], v[172:175], v[180:183], v[120:123]
	v_mfma_f32_16x16x32_bf16 v[112:115], v[152:155], v[196:199], v[112:115]
	v_mfma_f32_16x16x32_bf16 v[104:107], v[172:175], v[196:199], v[104:107]
	v_mfma_f32_16x16x32_bf16 v[96:99], v[152:155], v[216:219], v[96:99]
	v_mfma_f32_16x16x32_bf16 v[88:91], v[172:175], v[216:219], v[88:91]
	v_mfma_f32_16x16x32_bf16 v[80:83], v[152:155], v[224:227], v[80:83]
	v_mfma_f32_16x16x32_bf16 v[72:75], v[172:175], v[224:227], v[72:75]
	v_mfma_f32_16x16x32_bf16 v[128:131], v[156:159], v[192:195], v[128:131]
	v_mfma_f32_16x16x32_bf16 v[120:123], v[176:179], v[192:195], v[120:123]
	v_mfma_f32_16x16x32_bf16 v[112:115], v[156:159], v[212:215], v[112:115]
	v_mfma_f32_16x16x32_bf16 v[104:107], v[176:179], v[212:215], v[104:107]
	v_mfma_f32_16x16x32_bf16 v[96:99], v[156:159], v[220:223], v[96:99]
	v_mfma_f32_16x16x32_bf16 v[88:91], v[176:179], v[220:223], v[88:91]
	v_mfma_f32_16x16x32_bf16 v[80:83], v[156:159], v[242:245], v[80:83]
	v_mfma_f32_16x16x32_bf16 v[72:75], v[176:179], v[242:245], v[72:75]
	s_setprio 0
	s_barrier
; #define PG8_STAGE(bufoff, gbase, voff) do { _Pragma("unroll") for (int _i = 0; _i < 2; ++_i) \
;         __builtin_amdgcn_global_load_lds((const unsigned*)((const char*)(gbase) + (voff)[_i]), (PG8_LAS unsigned*)(lds + (bufoff) + ldsw + _i * 8192), 16, 0, 0); } while (0)
; #define PG8_LDA(dst, b, h) do { _Pragma("unroll") for (int m = 0; m < 4; ++m) _Pragma("unroll") for (int k = 0; k < 2; ++k) dst[m][k] = *(const PG8_LAS bf16x8*)(lds + PG8_SA(b, h) + aoff + m * 2048 + k * 1024); } while (0)
; #define PG8_MMA(ai, bj, At, Bt) do { __builtin_amdgcn_s_setprio(1); _Pragma("unroll") for (int m = 0; m < 4; ++m) _Pragma("unroll") for (int n = 0; n < 2; ++n) _Pragma("unroll") for (int k = 0; k < 2; ++k) \
;         acc[ai][bj][m][n] = __builtin_amdgcn_mfma_f32_16x16x32_bf16(Bt[n][k], At[m][k], acc[ai][bj][m][n], 0, 0, 0); __builtin_amdgcn_s_setprio(0); } while (0)
; #define PG8_WAIT_V(n) asm volatile("s_waitcnt vmcnt(" #n ")" ::: "memory")
; #define PG8_WAIT_L(n) asm volatile("s_waitcnt lgkmcnt(" #n ")" ::: "memory")
; #define PG8_BAR __builtin_amdgcn_s_barrier()
; #define PG8_SCHED __builtin_amdgcn_sched_barrier(0)
; template <class Epi, class Sched, bool ALIGN_EPI = false, bool SP2 = false>
; __device__ __forceinline__ void gemm_phase(PG8_LAS unsigned char* lds, const Gemm g, const Sched& S, const Epi& E) {
;     ...
;             PG8_WAIT_V(8); PG8_WAIT_L(0); PG8_BAR; PG8_MMA(0, 0, At, B0); PG8_MMA(0, 1, At, B1); PG8_BAR; PG8_SCHED;
;             PG8_LDA(At, 1, 1); PG8_STAGE(PG8_SB(1, 0), b3, voffB); PG8_STAGE(PG8_SB(1, 1), b3 + hstep, voffB); PG8_STAGE(PG8_SA(1, 0), a3, voffA);
;             PG8_WAIT_V(8); PG8_WAIT_L(0); PG8_BAR; PG8_MMA(1, 0, At, B0); PG8_MMA(1, 1, At, B1); PG8_BAR; PG8_SCHED;
;     ...
;         if constexpr (ALIGN_EPI) { if (wr == 0) PG8_BAR; }
;         if constexpr (!Epi::AFTER_DRAIN) { E(acc, cur, wr, wc, fr, fq); S.done(cur); }
;         if (!has_next) break;
	s_add_i32 s23, s23, s62
	v_lshl_add_u64 v[184:185], v[184:185], 0, s[76:77]
	s_mov_b32 m0, s23
	ds_read_b128 v[180:183], v191 offset:49152
	ds_read_b128 v[192:195], v191 offset:50176
	ds_read_b128 v[196:199], v191 offset:51200
	ds_read_b128 v[212:215], v191 offset:52224
	ds_read_b128 v[216:219], v191 offset:53248
	ds_read_b128 v[220:223], v191 offset:54272
	ds_read_b128 v[224:227], v191 offset:55296
	ds_read_b128 v[242:245], v191 offset:56320
	global_load_lds_dwordx4 v[184:185], off
	s_add_i32 m0, s23, 0x2000
	s_add_u32 s56, s56, 0x40080
	v_lshl_add_u64 v[184:185], v[238:239], 0, s[76:77]
	s_addc_u32 s57, s57, 0
	s_add_i32 s23, s80, s62
	global_load_lds_dwordx4 v[184:185], off
	v_lshl_add_u64 v[184:185], s[56:57], 0, v[162:163]
	s_mov_b32 m0, s23
	s_nop 0
	global_load_lds_dwordx4 v[184:185], off
	v_lshl_add_u64 v[184:185], s[56:57], 0, v[2:3]
	s_add_i32 m0, s23, 0x2000
	s_nop 0
	global_load_lds_dwordx4 v[184:185], off
	v_lshl_add_u64 v[184:185], v[240:241], 0, s[76:77]
	s_mov_b32 m0, s68
	s_nop 0
	global_load_lds_dwordx4 v[184:185], off
	v_lshl_add_u64 v[184:185], v[246:247], 0, s[76:77]
	s_mov_b32 m0, s69
	s_nop 0
	global_load_lds_dwordx4 v[184:185], off
	s_waitcnt vmcnt(8)
	s_waitcnt lgkmcnt(0)
	s_barrier
	s_setprio 1
	s_waitcnt lgkmcnt(0)
	v_mfma_f32_16x16x32_bf16 v[68:71], v[136:139], v[180:183], v[68:71]
	v_mfma_f32_16x16x32_bf16 v[60:63], v[144:147], v[180:183], v[60:63]
	v_mfma_f32_16x16x32_bf16 v[52:55], v[136:139], v[196:199], v[52:55]
	v_mfma_f32_16x16x32_bf16 v[44:47], v[144:147], v[196:199], v[44:47]
	v_mfma_f32_16x16x32_bf16 v[36:39], v[136:139], v[216:219], v[36:39]
	v_mfma_f32_16x16x32_bf16 v[28:31], v[144:147], v[216:219], v[28:31]
	v_mfma_f32_16x16x32_bf16 v[20:23], v[136:139], v[224:227], v[20:23]
	v_mfma_f32_16x16x32_bf16 v[12:15], v[144:147], v[224:227], v[12:15]
	v_mfma_f32_16x16x32_bf16 v[68:71], v[140:143], v[192:195], v[68:71]
	v_mfma_f32_16x16x32_bf16 v[60:63], v[148:151], v[192:195], v[60:63]
	v_mfma_f32_16x16x32_bf16 v[52:55], v[140:143], v[212:215], v[52:55]
	v_mfma_f32_16x16x32_bf16 v[44:47], v[148:151], v[212:215], v[44:47]
	v_mfma_f32_16x16x32_bf16 v[36:39], v[140:143], v[220:223], v[36:39]
	v_mfma_f32_16x16x32_bf16 v[28:31], v[148:151], v[220:223], v[28:31]
	v_mfma_f32_16x16x32_bf16 v[20:23], v[140:143], v[242:245], v[20:23]
	v_mfma_f32_16x16x32_bf16 v[12:15], v[148:151], v[242:245], v[12:15]
	s_setprio 0
	s_setprio 1
	v_mfma_f32_16x16x32_bf16 v[64:67], v[152:155], v[180:183], v[64:67]
	v_mfma_f32_16x16x32_bf16 v[56:59], v[172:175], v[180:183], v[56:59]
	v_mfma_f32_16x16x32_bf16 v[48:51], v[152:155], v[196:199], v[48:51]
	v_mfma_f32_16x16x32_bf16 v[40:43], v[172:175], v[196:199], v[40:43]
	v_mfma_f32_16x16x32_bf16 v[32:35], v[152:155], v[216:219], v[32:35]
	v_mfma_f32_16x16x32_bf16 v[24:27], v[172:175], v[216:219], v[24:27]
	v_mfma_f32_16x16x32_bf16 v[16:19], v[152:155], v[224:227], v[16:19]
	v_mfma_f32_16x16x32_bf16 v[8:11], v[172:175], v[224:227], v[8:11]
	v_mfma_f32_16x16x32_bf16 v[64:67], v[156:159], v[192:195], v[64:67]
	v_mfma_f32_16x16x32_bf16 v[56:59], v[176:179], v[192:195], v[56:59]
	v_mfma_f32_16x16x32_bf16 v[48:51], v[156:159], v[212:215], v[48:51]
	v_mfma_f32_16x16x32_bf16 v[40:43], v[176:179], v[212:215], v[40:43]
	v_mfma_f32_16x16x32_bf16 v[32:35], v[156:159], v[220:223], v[32:35]
	v_mfma_f32_16x16x32_bf16 v[24:27], v[176:179], v[220:223], v[24:27]
	v_mfma_f32_16x16x32_bf16 v[16:19], v[156:159], v[242:245], v[16:19]
	v_mfma_f32_16x16x32_bf16 v[8:11], v[176:179], v[242:245], v[8:11]
	s_setprio 0
	s_barrier
	s_add_i32 s79, s79, 2
	s_add_u32 s54, s54, 0x100
	s_addc_u32 s55, s55, 0
	s_add_u32 s75, s75, 0x100
	s_addc_u32 s78, s78, 0
	s_cmp_gt_u32 s79, 13
	s_cbranch_scc0 .LBB0_568
	s_and_b64 vcc, exec, s[44:45]
	s_cbranch_vccz .LBB0_571
	s_barrier
